# bundle: setprio-pair removal in all K-loops, first-iteration wait skipping in the three fused-RMSNorm GEMMs, grid barrier after phase 2 dropped
# baseline (speedup 1.0000x reference)
.LBB0_278:
	s_load_dwordx2 s[4:5], s[0:1], 0x78
	s_waitcnt lgkmcnt(0)
	s_cmp_gt_i32 s5, 3
	s_cselect_b64 s[4:5], -1, 0
	s_and_b64 s[2:3], s[2:3], s[4:5]
	s_andn2_b64 vcc, exec, s[2:3]
	s_branch .LBB0_328
	s_waitcnt vmcnt(0)
	v_cmp_eq_u32_e32 vcc, 0, v0
	s_barrier
	s_and_saveexec_b64 s[2:3], vcc
	s_cbranch_execz .LBB0_327
	v_readlane_b32 s4, v253, 14
	s_waitcnt vmcnt(0) expcnt(0) lgkmcnt(0)
	s_nop 0
	v_mov_b32_e32 v2, s4
	ds_read_b32 v4, v2
	ds_read_b32 v2, v2 offset:4
	s_waitcnt lgkmcnt(1)
	v_cmp_ne_u32_e32 vcc, 0, v4
	s_cbranch_vccnz .LBB0_295
	s_load_dwordx2 s[8:9], s[0:1], 0x80
	s_load_dword s7, s[0:1], 0x88
	s_add_u32 s4, s76, 0x4200
	s_addc_u32 s5, s77, 0
	s_add_u32 s6, s76, 0x4400
	s_waitcnt lgkmcnt(0)
	s_mul_i32 s33, s9, s8
	s_mul_i32 s33, s33, s7
	s_addc_u32 s7, s77, 0
	s_add_u32 s8, s76, 0x4500
	s_addc_u32 s9, s77, 0
	s_add_u32 s10, s76, 0x4600
	s_addc_u32 s11, s77, 0
	s_add_u32 s12, s76, 0x4700
	s_addc_u32 s13, s77, 0
	s_add_u32 s14, s76, 0x4800
	s_addc_u32 s15, s77, 0
	s_add_u32 s16, s76, 0x4900
	s_addc_u32 s17, s77, 0
	s_add_u32 s18, s76, 0x4a00
	s_addc_u32 s19, s77, 0
	s_add_u32 s22, s76, 0x4b00
	s_addc_u32 s23, s77, 0
	s_add_u32 s24, s76, 0x4c00
	s_addc_u32 s25, s77, 0
	s_add_u32 s26, s76, 0x4d00
	s_addc_u32 s27, s77, 0
	s_add_u32 s30, s76, 0x4e00
	s_addc_u32 s31, s77, 0
	s_add_u32 s34, s76, 0x4f00
	s_addc_u32 s35, s77, 0
	s_add_u32 s36, s76, 0x5000
	s_addc_u32 s37, s77, 0
	s_add_u32 s38, s76, 0x5100
	s_addc_u32 s39, s77, 0
	s_add_u32 s40, s76, 0x5200
	s_addc_u32 s41, s77, 0
	s_add_u32 s42, s76, 0x5300
	s_addc_u32 s43, s77, 0
	s_mov_b32 s50, 1
	v_mov_b32_e32 v18, 0
	s_branch .LBB0_283

.LBB0_738:
	s_cmp_eq_u32 s52, 0
	s_cselect_b32 s32, 1, 0
	s_and_b64 vcc, exec, s[52:53]
	s_mov_b64 s[60:61], s[22:23]
	s_mov_b32 s5, s20
	s_mov_b32 s6, s66
	s_mov_b32 s7, s20
	s_mov_b32 s8, s66
	s_cbranch_vccnz .LBB0_740
	s_ashr_i32 s51, s50, 31
	s_lshl_b64 s[60:61], s[50:51], 20
	s_mov_b32 s5, s50
	s_mov_b32 s6, s48
	s_mov_b32 s7, s94
	s_mov_b32 s8, s67

.LBB0_741:
	s_add_u32 s12, s36, 0xfff80080
	s_addc_u32 s13, s37, -1
	s_add_i32 s14, 0, 0x10000
	s_cmp_eq_u32 s11, 28
	s_cselect_b32 s63, s5, s13
	s_cselect_b32 s62, s6, s12
	s_cselect_b32 s39, s7, s10
	s_cselect_b32 s38, s8, s9
	s_add_i32 s15, 0, 0x14000
	v_add_u32_e32 v144, s14, v230
	v_add_u32_e32 v160, s15, v230
	ds_read_b128 v[124:127], v144
	ds_read_b128 v[128:131], v144 offset:1024
	ds_read_b128 v[136:139], v144 offset:2048
	ds_read_b128 v[144:147], v144 offset:3072
	ds_read_b128 v[148:151], v160
	ds_read_b128 v[152:155], v160 offset:1024
	ds_read_b128 v[156:159], v160 offset:2048
	ds_read_b128 v[160:163], v160 offset:3072
	v_lshl_add_u64 v[196:197], s[36:37], 0, v[222:223]
	s_add_i32 m0, s21, 0xc000
	ds_read_b128 v[164:167], v243
	ds_read_b128 v[168:171], v243 offset:1024
	ds_read_b128 v[172:175], v243 offset:2048
	ds_read_b128 v[176:179], v243 offset:3072
	ds_read_b128 v[180:183], v243 offset:4096
	ds_read_b128 v[184:187], v243 offset:5120
	ds_read_b128 v[188:191], v243 offset:6144
	ds_read_b128 v[192:195], v243 offset:7168
	global_load_lds_dwordx4 v[196:197], off
	v_lshl_add_u64 v[196:197], s[36:37], 0, v[220:221]
	s_add_i32 m0, s21, 0xe000
	s_nop 0
	global_load_lds_dwordx4 v[196:197], off
	s_cmp_lg_u32 s32, 0
	s_cbranch_scc1 .Lro_skip1
	s_waitcnt vmcnt(8)
.Lro_skip1:
	s_waitcnt lgkmcnt(0)
	s_barrier
	s_setprio 1
	s_waitcnt lgkmcnt(0)
	v_mfma_f32_16x16x32_bf16 v[140:143], v[124:127], v[164:167], v[140:143]
	v_mfma_f32_16x16x32_bf16 v[132:135], v[136:139], v[164:167], v[132:135]
	v_mfma_f32_16x16x32_bf16 v[112:115], v[124:127], v[172:175], v[112:115]
	v_mfma_f32_16x16x32_bf16 v[108:111], v[136:139], v[172:175], v[108:111]
	v_mfma_f32_16x16x32_bf16 v[96:99], v[124:127], v[180:183], v[96:99]
	v_mfma_f32_16x16x32_bf16 v[92:95], v[136:139], v[180:183], v[92:95]
	v_mfma_f32_16x16x32_bf16 v[80:83], v[124:127], v[188:191], v[80:83]
	v_mfma_f32_16x16x32_bf16 v[76:79], v[136:139], v[188:191], v[76:79]
	v_mfma_f32_16x16x32_bf16 v[140:143], v[128:131], v[168:171], v[140:143]
	v_mfma_f32_16x16x32_bf16 v[132:135], v[144:147], v[168:171], v[132:135]
	v_mfma_f32_16x16x32_bf16 v[112:115], v[128:131], v[176:179], v[112:115]
	v_mfma_f32_16x16x32_bf16 v[108:111], v[144:147], v[176:179], v[108:111]
	v_mfma_f32_16x16x32_bf16 v[96:99], v[128:131], v[184:187], v[96:99]
	v_mfma_f32_16x16x32_bf16 v[92:95], v[144:147], v[184:187], v[92:95]
	v_mfma_f32_16x16x32_bf16 v[80:83], v[128:131], v[192:195], v[80:83]
	v_mfma_f32_16x16x32_bf16 v[76:79], v[144:147], v[192:195], v[76:79]
	v_mfma_f32_16x16x32_bf16 v[120:123], v[148:151], v[164:167], v[120:123]
	v_mfma_f32_16x16x32_bf16 v[116:119], v[156:159], v[164:167], v[116:119]
	v_mfma_f32_16x16x32_bf16 v[104:107], v[148:151], v[172:175], v[104:107]
	v_mfma_f32_16x16x32_bf16 v[100:103], v[156:159], v[172:175], v[100:103]
	v_mfma_f32_16x16x32_bf16 v[88:91], v[148:151], v[180:183], v[88:91]
	v_mfma_f32_16x16x32_bf16 v[84:87], v[156:159], v[180:183], v[84:87]
	v_mfma_f32_16x16x32_bf16 v[72:75], v[148:151], v[188:191], v[72:75]
	v_mfma_f32_16x16x32_bf16 v[68:71], v[156:159], v[188:191], v[68:71]
	v_mfma_f32_16x16x32_bf16 v[120:123], v[152:155], v[168:171], v[120:123]
	v_mfma_f32_16x16x32_bf16 v[116:119], v[160:163], v[168:171], v[116:119]
	v_mfma_f32_16x16x32_bf16 v[104:107], v[152:155], v[176:179], v[104:107]
	v_mfma_f32_16x16x32_bf16 v[100:103], v[160:163], v[176:179], v[100:103]
	v_mfma_f32_16x16x32_bf16 v[88:91], v[152:155], v[184:187], v[88:91]
	v_mfma_f32_16x16x32_bf16 v[84:87], v[160:163], v[184:187], v[84:87]
	v_mfma_f32_16x16x32_bf16 v[72:75], v[152:155], v[192:195], v[72:75]
	v_mfma_f32_16x16x32_bf16 v[68:71], v[160:163], v[192:195], v[68:71]
	s_setprio 0
	s_barrier
	s_add_i32 s12, s14, s82
	v_lshl_add_u64 v[196:197], s[38:39], 0, v[2:3]
	s_mov_b32 m0, s12
	ds_read_b128 v[164:167], v243 offset:16384
	ds_read_b128 v[168:171], v243 offset:17408
	ds_read_b128 v[172:175], v243 offset:18432
	ds_read_b128 v[176:179], v243 offset:19456
	ds_read_b128 v[180:183], v243 offset:20480
	ds_read_b128 v[184:187], v243 offset:21504
	ds_read_b128 v[188:191], v243 offset:22528
	ds_read_b128 v[192:195], v243 offset:23552
	global_load_lds_dwordx4 v[196:197], off
	s_add_i32 m0, s12, 0x2000
	s_add_u32 s12, s38, 0x80000
	v_lshl_add_u64 v[198:199], s[38:39], 0, v[218:219]
	s_addc_u32 s13, s39, 0
	s_add_i32 s14, s15, s82
	global_load_lds_dwordx4 v[198:199], off
	v_lshl_add_u64 v[200:201], s[12:13], 0, v[2:3]
	s_mov_b32 m0, s14
	v_lshl_add_u64 v[202:203], s[62:63], 0, v[216:217]
	global_load_lds_dwordx4 v[200:201], off
	v_lshl_add_u64 v[200:201], s[12:13], 0, v[218:219]
	s_add_i32 m0, s14, 0x2000
	s_nop 0
	global_load_lds_dwordx4 v[200:201], off
	v_lshl_add_u64 v[200:201], s[62:63], 0, v[0:1]
	s_mov_b32 m0, s21
	s_nop 0
	global_load_lds_dwordx4 v[200:201], off
	s_mov_b32 m0, s83
	s_nop 0
	global_load_lds_dwordx4 v[202:203], off
	s_cmp_lg_u32 s32, 0
	s_cbranch_scc1 .Lro_skip2
	s_waitcnt vmcnt(8)
.Lro_skip2:
	s_mov_b32 s32, 0
	s_waitcnt lgkmcnt(0)
	s_barrier
	s_setprio 1
	s_waitcnt lgkmcnt(0)
	v_mfma_f32_16x16x32_bf16 v[64:67], v[124:127], v[164:167], v[64:67]
	v_mfma_f32_16x16x32_bf16 v[60:63], v[136:139], v[164:167], v[60:63]
	v_mfma_f32_16x16x32_bf16 v[48:51], v[124:127], v[172:175], v[48:51]
	v_mfma_f32_16x16x32_bf16 v[44:47], v[136:139], v[172:175], v[44:47]
	v_mfma_f32_16x16x32_bf16 v[32:35], v[124:127], v[180:183], v[32:35]
	v_mfma_f32_16x16x32_bf16 v[28:31], v[136:139], v[180:183], v[28:31]
	v_mfma_f32_16x16x32_bf16 v[16:19], v[124:127], v[188:191], v[16:19]
	v_mfma_f32_16x16x32_bf16 v[12:15], v[136:139], v[188:191], v[12:15]
	v_mfma_f32_16x16x32_bf16 v[64:67], v[128:131], v[168:171], v[64:67]
	v_mfma_f32_16x16x32_bf16 v[60:63], v[144:147], v[168:171], v[60:63]
	v_mfma_f32_16x16x32_bf16 v[48:51], v[128:131], v[176:179], v[48:51]
	v_mfma_f32_16x16x32_bf16 v[44:47], v[144:147], v[176:179], v[44:47]
	v_mfma_f32_16x16x32_bf16 v[32:35], v[128:131], v[184:187], v[32:35]
	v_mfma_f32_16x16x32_bf16 v[28:31], v[144:147], v[184:187], v[28:31]
	v_mfma_f32_16x16x32_bf16 v[16:19], v[128:131], v[192:195], v[16:19]
	v_mfma_f32_16x16x32_bf16 v[12:15], v[144:147], v[192:195], v[12:15]
	v_mfma_f32_16x16x32_bf16 v[56:59], v[148:151], v[164:167], v[56:59]
	v_mfma_f32_16x16x32_bf16 v[52:55], v[156:159], v[164:167], v[52:55]
	v_mfma_f32_16x16x32_bf16 v[40:43], v[148:151], v[172:175], v[40:43]
	v_mfma_f32_16x16x32_bf16 v[36:39], v[156:159], v[172:175], v[36:39]
	v_mfma_f32_16x16x32_bf16 v[24:27], v[148:151], v[180:183], v[24:27]
	v_mfma_f32_16x16x32_bf16 v[20:23], v[156:159], v[180:183], v[20:23]
	v_mfma_f32_16x16x32_bf16 v[8:11], v[148:151], v[188:191], v[8:11]
	v_mfma_f32_16x16x32_bf16 v[4:7], v[156:159], v[188:191], v[4:7]
	v_mfma_f32_16x16x32_bf16 v[56:59], v[152:155], v[168:171], v[56:59]
	v_mfma_f32_16x16x32_bf16 v[52:55], v[160:163], v[168:171], v[52:55]
	v_mfma_f32_16x16x32_bf16 v[40:43], v[152:155], v[176:179], v[40:43]
	v_mfma_f32_16x16x32_bf16 v[36:39], v[160:163], v[176:179], v[36:39]
	v_mfma_f32_16x16x32_bf16 v[24:27], v[152:155], v[184:187], v[24:27]
	v_mfma_f32_16x16x32_bf16 v[20:23], v[160:163], v[184:187], v[20:23]
	v_mfma_f32_16x16x32_bf16 v[8:11], v[152:155], v[192:195], v[8:11]
	v_mfma_f32_16x16x32_bf16 v[4:7], v[160:163], v[192:195], v[4:7]
	s_setprio 0
	s_barrier
	s_add_i32 s14, 0, 0x18000
	s_add_i32 s15, 0, 0x1c000
	v_add_u32_e32 v144, s14, v230
	v_add_u32_e32 v160, s15, v230
	ds_read_b128 v[124:127], v144
	ds_read_b128 v[128:131], v144 offset:1024
	ds_read_b128 v[136:139], v144 offset:2048
	ds_read_b128 v[144:147], v144 offset:3072
	ds_read_b128 v[148:151], v160
	ds_read_b128 v[152:155], v160 offset:1024
	ds_read_b128 v[156:159], v160 offset:2048
	ds_read_b128 v[160:163], v160 offset:3072
	s_add_u32 s12, s62, 0x80000
	s_addc_u32 s13, s63, 0
	s_mov_b32 m0, s84
	v_lshl_add_u64 v[204:205], s[12:13], 0, v[0:1]
	ds_read_b128 v[164:167], v243 offset:32768
	ds_read_b128 v[168:171], v243 offset:33792
	ds_read_b128 v[172:175], v243 offset:34816
	ds_read_b128 v[176:179], v243 offset:35840
	ds_read_b128 v[180:183], v243 offset:36864
	ds_read_b128 v[184:187], v243 offset:37888
	ds_read_b128 v[188:191], v243 offset:38912
	ds_read_b128 v[192:195], v243 offset:39936
	global_load_lds_dwordx4 v[204:205], off
	v_lshl_add_u64 v[204:205], s[12:13], 0, v[216:217]
	s_mov_b32 m0, s85
	s_nop 0
	global_load_lds_dwordx4 v[204:205], off
	s_waitcnt vmcnt(8)
	s_waitcnt lgkmcnt(0)
	s_barrier
	s_setprio 1
	s_waitcnt lgkmcnt(0)
	v_mfma_f32_16x16x32_bf16 v[140:143], v[124:127], v[164:167], v[140:143]
	v_mfma_f32_16x16x32_bf16 v[132:135], v[136:139], v[164:167], v[132:135]
	v_mfma_f32_16x16x32_bf16 v[112:115], v[124:127], v[172:175], v[112:115]
	v_mfma_f32_16x16x32_bf16 v[108:111], v[136:139], v[172:175], v[108:111]
	v_mfma_f32_16x16x32_bf16 v[96:99], v[124:127], v[180:183], v[96:99]
	v_mfma_f32_16x16x32_bf16 v[92:95], v[136:139], v[180:183], v[92:95]
	v_mfma_f32_16x16x32_bf16 v[80:83], v[124:127], v[188:191], v[80:83]
	v_mfma_f32_16x16x32_bf16 v[76:79], v[136:139], v[188:191], v[76:79]
	v_mfma_f32_16x16x32_bf16 v[140:143], v[128:131], v[168:171], v[140:143]
	v_mfma_f32_16x16x32_bf16 v[132:135], v[144:147], v[168:171], v[132:135]
	v_mfma_f32_16x16x32_bf16 v[112:115], v[128:131], v[176:179], v[112:115]
	v_mfma_f32_16x16x32_bf16 v[108:111], v[144:147], v[176:179], v[108:111]
	v_mfma_f32_16x16x32_bf16 v[96:99], v[128:131], v[184:187], v[96:99]
	v_mfma_f32_16x16x32_bf16 v[92:95], v[144:147], v[184:187], v[92:95]
	v_mfma_f32_16x16x32_bf16 v[80:83], v[128:131], v[192:195], v[80:83]
	v_mfma_f32_16x16x32_bf16 v[76:79], v[144:147], v[192:195], v[76:79]
	v_mfma_f32_16x16x32_bf16 v[120:123], v[148:151], v[164:167], v[120:123]
	v_mfma_f32_16x16x32_bf16 v[116:119], v[156:159], v[164:167], v[116:119]
	v_mfma_f32_16x16x32_bf16 v[104:107], v[148:151], v[172:175], v[104:107]
	v_mfma_f32_16x16x32_bf16 v[100:103], v[156:159], v[172:175], v[100:103]
	v_mfma_f32_16x16x32_bf16 v[88:91], v[148:151], v[180:183], v[88:91]
	v_mfma_f32_16x16x32_bf16 v[84:87], v[156:159], v[180:183], v[84:87]
	v_mfma_f32_16x16x32_bf16 v[72:75], v[148:151], v[188:191], v[72:75]
	v_mfma_f32_16x16x32_bf16 v[68:71], v[156:159], v[188:191], v[68:71]
	v_mfma_f32_16x16x32_bf16 v[120:123], v[152:155], v[168:171], v[120:123]
	v_mfma_f32_16x16x32_bf16 v[116:119], v[160:163], v[168:171], v[116:119]
	v_mfma_f32_16x16x32_bf16 v[104:107], v[152:155], v[176:179], v[104:107]
	v_mfma_f32_16x16x32_bf16 v[100:103], v[160:163], v[176:179], v[100:103]
	v_mfma_f32_16x16x32_bf16 v[88:91], v[152:155], v[184:187], v[88:91]
	v_mfma_f32_16x16x32_bf16 v[84:87], v[160:163], v[184:187], v[84:87]
	v_mfma_f32_16x16x32_bf16 v[72:75], v[152:155], v[192:195], v[72:75]
	v_mfma_f32_16x16x32_bf16 v[68:71], v[160:163], v[192:195], v[68:71]
	s_setprio 0
	s_barrier
	s_add_i32 s12, s14, s82
	v_lshl_add_u64 v[196:197], v[196:197], 0, s[68:69]
	s_mov_b32 m0, s12
	ds_read_b128 v[164:167], v243 offset:49152
	ds_read_b128 v[168:171], v243 offset:50176
	ds_read_b128 v[172:175], v243 offset:51200
	ds_read_b128 v[176:179], v243 offset:52224
	ds_read_b128 v[180:183], v243 offset:53248
	ds_read_b128 v[184:187], v243 offset:54272
	ds_read_b128 v[188:191], v243 offset:55296
	ds_read_b128 v[192:195], v243 offset:56320
	global_load_lds_dwordx4 v[196:197], off
	s_add_i32 m0, s12, 0x2000
	s_add_u32 s12, s38, 0x80080
	v_lshl_add_u64 v[196:197], v[198:199], 0, s[68:69]
	s_addc_u32 s13, s39, 0
	s_add_i32 s14, s15, s82
	global_load_lds_dwordx4 v[196:197], off
	v_lshl_add_u64 v[196:197], s[12:13], 0, v[2:3]
	s_mov_b32 m0, s14
	s_nop 0
	global_load_lds_dwordx4 v[196:197], off
	v_lshl_add_u64 v[196:197], s[12:13], 0, v[218:219]
	s_add_i32 m0, s14, 0x2000
	s_nop 0
	global_load_lds_dwordx4 v[196:197], off
	v_lshl_add_u64 v[196:197], v[200:201], 0, s[68:69]
	s_mov_b32 m0, s89
	s_nop 0
	global_load_lds_dwordx4 v[196:197], off
	v_lshl_add_u64 v[196:197], v[202:203], 0, s[68:69]
	s_mov_b32 m0, s90
	s_nop 0
	global_load_lds_dwordx4 v[196:197], off
	s_waitcnt vmcnt(8)
	s_waitcnt lgkmcnt(0)
	s_barrier
	s_setprio 1
	s_waitcnt lgkmcnt(0)
	v_mfma_f32_16x16x32_bf16 v[64:67], v[124:127], v[164:167], v[64:67]
	v_mfma_f32_16x16x32_bf16 v[60:63], v[136:139], v[164:167], v[60:63]
	v_mfma_f32_16x16x32_bf16 v[48:51], v[124:127], v[172:175], v[48:51]
	v_mfma_f32_16x16x32_bf16 v[44:47], v[136:139], v[172:175], v[44:47]
	v_mfma_f32_16x16x32_bf16 v[32:35], v[124:127], v[180:183], v[32:35]
	v_mfma_f32_16x16x32_bf16 v[28:31], v[136:139], v[180:183], v[28:31]
	v_mfma_f32_16x16x32_bf16 v[16:19], v[124:127], v[188:191], v[16:19]
	v_mfma_f32_16x16x32_bf16 v[12:15], v[136:139], v[188:191], v[12:15]
	v_mfma_f32_16x16x32_bf16 v[64:67], v[128:131], v[168:171], v[64:67]
	v_mfma_f32_16x16x32_bf16 v[60:63], v[144:147], v[168:171], v[60:63]
	v_mfma_f32_16x16x32_bf16 v[48:51], v[128:131], v[176:179], v[48:51]
	v_mfma_f32_16x16x32_bf16 v[44:47], v[144:147], v[176:179], v[44:47]
	v_mfma_f32_16x16x32_bf16 v[32:35], v[128:131], v[184:187], v[32:35]
	v_mfma_f32_16x16x32_bf16 v[28:31], v[144:147], v[184:187], v[28:31]
	v_mfma_f32_16x16x32_bf16 v[16:19], v[128:131], v[192:195], v[16:19]
	v_mfma_f32_16x16x32_bf16 v[12:15], v[144:147], v[192:195], v[12:15]
	v_mfma_f32_16x16x32_bf16 v[56:59], v[148:151], v[164:167], v[56:59]
	v_mfma_f32_16x16x32_bf16 v[52:55], v[156:159], v[164:167], v[52:55]
	v_mfma_f32_16x16x32_bf16 v[40:43], v[148:151], v[172:175], v[40:43]
	v_mfma_f32_16x16x32_bf16 v[36:39], v[156:159], v[172:175], v[36:39]
	v_mfma_f32_16x16x32_bf16 v[24:27], v[148:151], v[180:183], v[24:27]
	v_mfma_f32_16x16x32_bf16 v[20:23], v[156:159], v[180:183], v[20:23]
	v_mfma_f32_16x16x32_bf16 v[8:11], v[148:151], v[188:191], v[8:11]
	v_mfma_f32_16x16x32_bf16 v[4:7], v[156:159], v[188:191], v[4:7]
	v_mfma_f32_16x16x32_bf16 v[56:59], v[152:155], v[168:171], v[56:59]
	v_mfma_f32_16x16x32_bf16 v[52:55], v[160:163], v[168:171], v[52:55]
	v_mfma_f32_16x16x32_bf16 v[40:43], v[152:155], v[176:179], v[40:43]
	v_mfma_f32_16x16x32_bf16 v[36:39], v[160:163], v[176:179], v[36:39]
	v_mfma_f32_16x16x32_bf16 v[24:27], v[152:155], v[184:187], v[24:27]
	v_mfma_f32_16x16x32_bf16 v[20:23], v[160:163], v[184:187], v[20:23]
	v_mfma_f32_16x16x32_bf16 v[8:11], v[152:155], v[192:195], v[8:11]
	v_mfma_f32_16x16x32_bf16 v[4:7], v[160:163], v[192:195], v[4:7]
	s_setprio 0
	s_barrier
	s_add_i32 s11, s11, 2
	s_add_u32 s9, s9, 0x100
	s_addc_u32 s10, s10, 0
	s_add_u32 s36, s36, 0x100
	s_addc_u32 s37, s37, 0
	s_cmp_gt_u32 s11, 29
	s_cbranch_scc0 .LBB0_741
	s_and_b64 vcc, exec, s[46:47]
	s_cbranch_vccz .LBB0_744
	s_barrier

.LBB0_946:
	s_cmp_eq_u32 s56, 0
	s_cselect_b32 s32, 1, 0
	s_ashr_i32 s49, s48, 31
	s_andn2_b64 vcc, exec, s[56:57]
	s_lshl_b64 s[6:7], s[48:49], 19
	s_add_u32 s52, s62, s6
	s_addc_u32 s53, s63, s7
	s_and_b64 s[6:7], s[56:57], exec
	s_cselect_b32 s5, s53, s41
	s_cselect_b32 s6, s52, s40
	s_ashr_i32 s51, s50, 31
	s_lshl_b64 s[8:9], s[50:51], 19
	s_add_u32 s54, s64, s8
	s_addc_u32 s55, s65, s9
	s_and_b64 s[8:9], s[56:57], exec
	s_cselect_b32 s7, s55, s39
	s_cselect_b32 s8, s54, s38
	s_add_u32 s9, s38, 0x100
	v_cndmask_b32_e64 v4, 0, 1, s[56:57]
	s_addc_u32 s10, s39, 0
	v_cmp_ne_u32_e64 s[36:37], 1, v4
	s_add_u32 s38, s40, 0x40080
	v_mov_b32_e32 v4, 0
	s_addc_u32 s39, s41, 0
	s_mov_b32 s11, -2
	s_waitcnt lgkmcnt(0)
	v_mov_b32_e32 v5, v4
	v_mov_b32_e32 v6, v4
	v_mov_b32_e32 v7, v4
	v_mov_b32_e32 v8, v4
	v_mov_b32_e32 v9, v4
	v_mov_b32_e32 v10, v4
	v_mov_b32_e32 v11, v4
	v_mov_b32_e32 v20, v4
	v_mov_b32_e32 v21, v4
	v_mov_b32_e32 v22, v4
	v_mov_b32_e32 v23, v4
	v_mov_b32_e32 v24, v4
	v_mov_b32_e32 v25, v4
	v_mov_b32_e32 v26, v4
	v_mov_b32_e32 v27, v4
	v_mov_b32_e32 v36, v4
	v_mov_b32_e32 v37, v4
	v_mov_b32_e32 v38, v4
	v_mov_b32_e32 v39, v4
	v_mov_b32_e32 v40, v4
	v_mov_b32_e32 v41, v4
	v_mov_b32_e32 v42, v4
	v_mov_b32_e32 v43, v4
	v_mov_b32_e32 v52, v4
	v_mov_b32_e32 v53, v4
	v_mov_b32_e32 v54, v4
	v_mov_b32_e32 v55, v4
	v_mov_b32_e32 v56, v4
	v_mov_b32_e32 v57, v4
	v_mov_b32_e32 v58, v4
	v_mov_b32_e32 v59, v4
	v_mov_b32_e32 v12, v4
	v_mov_b32_e32 v13, v4
	v_mov_b32_e32 v14, v4
	v_mov_b32_e32 v15, v4
	v_mov_b32_e32 v16, v4
	v_mov_b32_e32 v17, v4
	v_mov_b32_e32 v18, v4
	v_mov_b32_e32 v19, v4
	v_mov_b32_e32 v28, v4
	v_mov_b32_e32 v29, v4
	v_mov_b32_e32 v30, v4
	v_mov_b32_e32 v31, v4
	v_mov_b32_e32 v32, v4
	v_mov_b32_e32 v33, v4
	v_mov_b32_e32 v34, v4
	v_mov_b32_e32 v35, v4
	v_mov_b32_e32 v44, v4
	v_mov_b32_e32 v45, v4
	v_mov_b32_e32 v46, v4
	v_mov_b32_e32 v47, v4
	v_mov_b32_e32 v48, v4
	v_mov_b32_e32 v49, v4
	v_mov_b32_e32 v50, v4
	v_mov_b32_e32 v51, v4
	v_mov_b32_e32 v60, v4
	v_mov_b32_e32 v61, v4
	v_mov_b32_e32 v62, v4
	v_mov_b32_e32 v63, v4
	v_mov_b32_e32 v64, v4
	v_mov_b32_e32 v65, v4
	v_mov_b32_e32 v66, v4
	v_mov_b32_e32 v67, v4
	v_mov_b32_e32 v68, v4
	v_mov_b32_e32 v69, v4
	v_mov_b32_e32 v70, v4
	v_mov_b32_e32 v71, v4
	v_mov_b32_e32 v72, v4
	v_mov_b32_e32 v73, v4
	v_mov_b32_e32 v74, v4
	v_mov_b32_e32 v75, v4
	v_mov_b32_e32 v84, v4
	v_mov_b32_e32 v85, v4
	v_mov_b32_e32 v86, v4
	v_mov_b32_e32 v87, v4
	v_mov_b32_e32 v88, v4
	v_mov_b32_e32 v89, v4
	v_mov_b32_e32 v90, v4
	v_mov_b32_e32 v91, v4
	v_mov_b32_e32 v100, v4
	v_mov_b32_e32 v101, v4
	v_mov_b32_e32 v102, v4
	v_mov_b32_e32 v103, v4
	v_mov_b32_e32 v104, v4
	v_mov_b32_e32 v105, v4
	v_mov_b32_e32 v106, v4
	v_mov_b32_e32 v107, v4
	v_mov_b32_e32 v116, v4
	v_mov_b32_e32 v117, v4
	v_mov_b32_e32 v118, v4
	v_mov_b32_e32 v119, v4
	v_mov_b32_e32 v120, v4
	v_mov_b32_e32 v121, v4
	v_mov_b32_e32 v122, v4
	v_mov_b32_e32 v123, v4
	v_mov_b32_e32 v76, v4
	v_mov_b32_e32 v77, v4
	v_mov_b32_e32 v78, v4
	v_mov_b32_e32 v79, v4
	v_mov_b32_e32 v80, v4
	v_mov_b32_e32 v81, v4
	v_mov_b32_e32 v82, v4
	v_mov_b32_e32 v83, v4
	v_mov_b32_e32 v92, v4
	v_mov_b32_e32 v93, v4
	v_mov_b32_e32 v94, v4
	v_mov_b32_e32 v95, v4
	v_mov_b32_e32 v96, v4
	v_mov_b32_e32 v97, v4
	v_mov_b32_e32 v98, v4
	v_mov_b32_e32 v99, v4
	v_mov_b32_e32 v108, v4
	v_mov_b32_e32 v109, v4
	v_mov_b32_e32 v110, v4
	v_mov_b32_e32 v111, v4
	v_mov_b32_e32 v112, v4
	v_mov_b32_e32 v113, v4
	v_mov_b32_e32 v114, v4
	v_mov_b32_e32 v115, v4
	v_mov_b32_e32 v132, v4
	v_mov_b32_e32 v133, v4
	v_mov_b32_e32 v134, v4
	v_mov_b32_e32 v135, v4
	v_mov_b32_e32 v140, v4
	v_mov_b32_e32 v141, v4
	v_mov_b32_e32 v142, v4
	v_mov_b32_e32 v143, v4
.LBB0_947:
	s_add_u32 s12, s38, 0xfffc0080
	s_addc_u32 s13, s39, -1
	s_add_i32 s14, 0, 0x10000
	s_cmp_eq_u32 s11, 12
	s_cselect_b32 s57, s5, s13
	s_cselect_b32 s56, s6, s12
	s_cselect_b32 s41, s7, s10
	s_cselect_b32 s40, s8, s9
	s_add_i32 s15, 0, 0x14000
	v_add_u32_e32 v144, s14, v230
	v_add_u32_e32 v160, s15, v230
	ds_read_b128 v[124:127], v144
	ds_read_b128 v[128:131], v144 offset:1024
	ds_read_b128 v[136:139], v144 offset:2048
	ds_read_b128 v[144:147], v144 offset:3072
	ds_read_b128 v[148:151], v160
	ds_read_b128 v[152:155], v160 offset:1024
	ds_read_b128 v[156:159], v160 offset:2048
	ds_read_b128 v[160:163], v160 offset:3072
	v_lshl_add_u64 v[196:197], s[38:39], 0, v[222:223]
	s_add_i32 m0, s71, 0xc000
	ds_read_b128 v[164:167], v243
	ds_read_b128 v[168:171], v243 offset:1024
	ds_read_b128 v[172:175], v243 offset:2048
	ds_read_b128 v[176:179], v243 offset:3072
	ds_read_b128 v[180:183], v243 offset:4096
	ds_read_b128 v[184:187], v243 offset:5120
	ds_read_b128 v[188:191], v243 offset:6144
	ds_read_b128 v[192:195], v243 offset:7168
	global_load_lds_dwordx4 v[196:197], off
	v_lshl_add_u64 v[196:197], s[38:39], 0, v[220:221]
	s_add_i32 m0, s71, 0xe000
	s_nop 0
	global_load_lds_dwordx4 v[196:197], off
	s_cmp_lg_u32 s32, 0
	s_cbranch_scc1 .Lrp_skip1
	s_waitcnt vmcnt(8)
.Lrp_skip1:
	s_waitcnt lgkmcnt(0)
	s_barrier
	s_setprio 1
	s_waitcnt lgkmcnt(0)
	v_mfma_f32_16x16x32_bf16 v[140:143], v[124:127], v[164:167], v[140:143]
	v_mfma_f32_16x16x32_bf16 v[132:135], v[136:139], v[164:167], v[132:135]
	v_mfma_f32_16x16x32_bf16 v[112:115], v[124:127], v[172:175], v[112:115]
	v_mfma_f32_16x16x32_bf16 v[108:111], v[136:139], v[172:175], v[108:111]
	v_mfma_f32_16x16x32_bf16 v[96:99], v[124:127], v[180:183], v[96:99]
	v_mfma_f32_16x16x32_bf16 v[92:95], v[136:139], v[180:183], v[92:95]
	v_mfma_f32_16x16x32_bf16 v[80:83], v[124:127], v[188:191], v[80:83]
	v_mfma_f32_16x16x32_bf16 v[76:79], v[136:139], v[188:191], v[76:79]
	v_mfma_f32_16x16x32_bf16 v[140:143], v[128:131], v[168:171], v[140:143]
	v_mfma_f32_16x16x32_bf16 v[132:135], v[144:147], v[168:171], v[132:135]
	v_mfma_f32_16x16x32_bf16 v[112:115], v[128:131], v[176:179], v[112:115]
	v_mfma_f32_16x16x32_bf16 v[108:111], v[144:147], v[176:179], v[108:111]
	v_mfma_f32_16x16x32_bf16 v[96:99], v[128:131], v[184:187], v[96:99]
	v_mfma_f32_16x16x32_bf16 v[92:95], v[144:147], v[184:187], v[92:95]
	v_mfma_f32_16x16x32_bf16 v[80:83], v[128:131], v[192:195], v[80:83]
	v_mfma_f32_16x16x32_bf16 v[76:79], v[144:147], v[192:195], v[76:79]
	v_mfma_f32_16x16x32_bf16 v[120:123], v[148:151], v[164:167], v[120:123]
	v_mfma_f32_16x16x32_bf16 v[116:119], v[156:159], v[164:167], v[116:119]
	v_mfma_f32_16x16x32_bf16 v[104:107], v[148:151], v[172:175], v[104:107]
	v_mfma_f32_16x16x32_bf16 v[100:103], v[156:159], v[172:175], v[100:103]
	v_mfma_f32_16x16x32_bf16 v[88:91], v[148:151], v[180:183], v[88:91]
	v_mfma_f32_16x16x32_bf16 v[84:87], v[156:159], v[180:183], v[84:87]
	v_mfma_f32_16x16x32_bf16 v[72:75], v[148:151], v[188:191], v[72:75]
	v_mfma_f32_16x16x32_bf16 v[68:71], v[156:159], v[188:191], v[68:71]
	v_mfma_f32_16x16x32_bf16 v[120:123], v[152:155], v[168:171], v[120:123]
	v_mfma_f32_16x16x32_bf16 v[116:119], v[160:163], v[168:171], v[116:119]
	v_mfma_f32_16x16x32_bf16 v[104:107], v[152:155], v[176:179], v[104:107]
	v_mfma_f32_16x16x32_bf16 v[100:103], v[160:163], v[176:179], v[100:103]
	v_mfma_f32_16x16x32_bf16 v[88:91], v[152:155], v[184:187], v[88:91]
	v_mfma_f32_16x16x32_bf16 v[84:87], v[160:163], v[184:187], v[84:87]
	v_mfma_f32_16x16x32_bf16 v[72:75], v[152:155], v[192:195], v[72:75]
	v_mfma_f32_16x16x32_bf16 v[68:71], v[160:163], v[192:195], v[68:71]
	s_setprio 0
	s_barrier
	s_add_i32 s12, s14, s70
	v_lshl_add_u64 v[196:197], s[40:41], 0, v[2:3]
	s_mov_b32 m0, s12
	ds_read_b128 v[164:167], v243 offset:16384
	ds_read_b128 v[168:171], v243 offset:17408
	ds_read_b128 v[172:175], v243 offset:18432
	ds_read_b128 v[176:179], v243 offset:19456
	ds_read_b128 v[180:183], v243 offset:20480
	ds_read_b128 v[184:187], v243 offset:21504
	ds_read_b128 v[188:191], v243 offset:22528
	ds_read_b128 v[192:195], v243 offset:23552
	global_load_lds_dwordx4 v[196:197], off
	s_add_i32 m0, s12, 0x2000
	s_add_u32 s12, s40, 0x40000
	v_lshl_add_u64 v[198:199], s[40:41], 0, v[218:219]
	s_addc_u32 s13, s41, 0
	s_add_i32 s14, s15, s70
	global_load_lds_dwordx4 v[198:199], off
	v_lshl_add_u64 v[200:201], s[12:13], 0, v[2:3]
	s_mov_b32 m0, s14
	v_lshl_add_u64 v[202:203], s[56:57], 0, v[216:217]
	global_load_lds_dwordx4 v[200:201], off
	v_lshl_add_u64 v[200:201], s[12:13], 0, v[218:219]
	s_add_i32 m0, s14, 0x2000
	s_nop 0
	global_load_lds_dwordx4 v[200:201], off
	v_lshl_add_u64 v[200:201], s[56:57], 0, v[0:1]
	s_mov_b32 m0, s71
	s_nop 0
	global_load_lds_dwordx4 v[200:201], off
	s_mov_b32 m0, s80
	s_nop 0
	global_load_lds_dwordx4 v[202:203], off
	s_cmp_lg_u32 s32, 0
	s_cbranch_scc1 .Lrp_skip2
	s_waitcnt vmcnt(8)
.Lrp_skip2:
	s_mov_b32 s32, 0
	s_waitcnt lgkmcnt(0)
	s_barrier
	s_setprio 1
	s_waitcnt lgkmcnt(0)
	v_mfma_f32_16x16x32_bf16 v[64:67], v[124:127], v[164:167], v[64:67]
	v_mfma_f32_16x16x32_bf16 v[60:63], v[136:139], v[164:167], v[60:63]
	v_mfma_f32_16x16x32_bf16 v[48:51], v[124:127], v[172:175], v[48:51]
	v_mfma_f32_16x16x32_bf16 v[44:47], v[136:139], v[172:175], v[44:47]
	v_mfma_f32_16x16x32_bf16 v[32:35], v[124:127], v[180:183], v[32:35]
	v_mfma_f32_16x16x32_bf16 v[28:31], v[136:139], v[180:183], v[28:31]
	v_mfma_f32_16x16x32_bf16 v[16:19], v[124:127], v[188:191], v[16:19]
	v_mfma_f32_16x16x32_bf16 v[12:15], v[136:139], v[188:191], v[12:15]
	v_mfma_f32_16x16x32_bf16 v[64:67], v[128:131], v[168:171], v[64:67]
	v_mfma_f32_16x16x32_bf16 v[60:63], v[144:147], v[168:171], v[60:63]
	v_mfma_f32_16x16x32_bf16 v[48:51], v[128:131], v[176:179], v[48:51]
	v_mfma_f32_16x16x32_bf16 v[44:47], v[144:147], v[176:179], v[44:47]
	v_mfma_f32_16x16x32_bf16 v[32:35], v[128:131], v[184:187], v[32:35]
	v_mfma_f32_16x16x32_bf16 v[28:31], v[144:147], v[184:187], v[28:31]
	v_mfma_f32_16x16x32_bf16 v[16:19], v[128:131], v[192:195], v[16:19]
	v_mfma_f32_16x16x32_bf16 v[12:15], v[144:147], v[192:195], v[12:15]
	v_mfma_f32_16x16x32_bf16 v[56:59], v[148:151], v[164:167], v[56:59]
	v_mfma_f32_16x16x32_bf16 v[52:55], v[156:159], v[164:167], v[52:55]
	v_mfma_f32_16x16x32_bf16 v[40:43], v[148:151], v[172:175], v[40:43]
	v_mfma_f32_16x16x32_bf16 v[36:39], v[156:159], v[172:175], v[36:39]
	v_mfma_f32_16x16x32_bf16 v[24:27], v[148:151], v[180:183], v[24:27]
	v_mfma_f32_16x16x32_bf16 v[20:23], v[156:159], v[180:183], v[20:23]
	v_mfma_f32_16x16x32_bf16 v[8:11], v[148:151], v[188:191], v[8:11]
	v_mfma_f32_16x16x32_bf16 v[4:7], v[156:159], v[188:191], v[4:7]
	v_mfma_f32_16x16x32_bf16 v[56:59], v[152:155], v[168:171], v[56:59]
	v_mfma_f32_16x16x32_bf16 v[52:55], v[160:163], v[168:171], v[52:55]
	v_mfma_f32_16x16x32_bf16 v[40:43], v[152:155], v[176:179], v[40:43]
	v_mfma_f32_16x16x32_bf16 v[36:39], v[160:163], v[176:179], v[36:39]
	v_mfma_f32_16x16x32_bf16 v[24:27], v[152:155], v[184:187], v[24:27]
	v_mfma_f32_16x16x32_bf16 v[20:23], v[160:163], v[184:187], v[20:23]
	v_mfma_f32_16x16x32_bf16 v[8:11], v[152:155], v[192:195], v[8:11]
	v_mfma_f32_16x16x32_bf16 v[4:7], v[160:163], v[192:195], v[4:7]
	s_setprio 0
	s_barrier
	s_add_i32 s14, 0, 0x18000
	s_add_i32 s15, 0, 0x1c000
	v_add_u32_e32 v144, s14, v230
	v_add_u32_e32 v160, s15, v230
	ds_read_b128 v[124:127], v144
	ds_read_b128 v[128:131], v144 offset:1024
	ds_read_b128 v[136:139], v144 offset:2048
	ds_read_b128 v[144:147], v144 offset:3072
	ds_read_b128 v[148:151], v160
	ds_read_b128 v[152:155], v160 offset:1024
	ds_read_b128 v[156:159], v160 offset:2048
	ds_read_b128 v[160:163], v160 offset:3072
	s_add_u32 s12, s56, 0x40000
	s_addc_u32 s13, s57, 0
	s_mov_b32 m0, s81
	v_lshl_add_u64 v[204:205], s[12:13], 0, v[0:1]
	ds_read_b128 v[164:167], v243 offset:32768
	ds_read_b128 v[168:171], v243 offset:33792
	ds_read_b128 v[172:175], v243 offset:34816
	ds_read_b128 v[176:179], v243 offset:35840
	ds_read_b128 v[180:183], v243 offset:36864
	ds_read_b128 v[184:187], v243 offset:37888
	ds_read_b128 v[188:191], v243 offset:38912
	ds_read_b128 v[192:195], v243 offset:39936
	global_load_lds_dwordx4 v[204:205], off
	v_lshl_add_u64 v[204:205], s[12:13], 0, v[216:217]
	s_mov_b32 m0, s82
	s_nop 0
	global_load_lds_dwordx4 v[204:205], off
	s_waitcnt vmcnt(8)
	s_waitcnt lgkmcnt(0)
	s_barrier
	s_setprio 1
	s_waitcnt lgkmcnt(0)
	v_mfma_f32_16x16x32_bf16 v[140:143], v[124:127], v[164:167], v[140:143]
	v_mfma_f32_16x16x32_bf16 v[132:135], v[136:139], v[164:167], v[132:135]
	v_mfma_f32_16x16x32_bf16 v[112:115], v[124:127], v[172:175], v[112:115]
	v_mfma_f32_16x16x32_bf16 v[108:111], v[136:139], v[172:175], v[108:111]
	v_mfma_f32_16x16x32_bf16 v[96:99], v[124:127], v[180:183], v[96:99]
	v_mfma_f32_16x16x32_bf16 v[92:95], v[136:139], v[180:183], v[92:95]
	v_mfma_f32_16x16x32_bf16 v[80:83], v[124:127], v[188:191], v[80:83]
	v_mfma_f32_16x16x32_bf16 v[76:79], v[136:139], v[188:191], v[76:79]
	v_mfma_f32_16x16x32_bf16 v[140:143], v[128:131], v[168:171], v[140:143]
	v_mfma_f32_16x16x32_bf16 v[132:135], v[144:147], v[168:171], v[132:135]
	v_mfma_f32_16x16x32_bf16 v[112:115], v[128:131], v[176:179], v[112:115]
	v_mfma_f32_16x16x32_bf16 v[108:111], v[144:147], v[176:179], v[108:111]
	v_mfma_f32_16x16x32_bf16 v[96:99], v[128:131], v[184:187], v[96:99]
	v_mfma_f32_16x16x32_bf16 v[92:95], v[144:147], v[184:187], v[92:95]
	v_mfma_f32_16x16x32_bf16 v[80:83], v[128:131], v[192:195], v[80:83]
	v_mfma_f32_16x16x32_bf16 v[76:79], v[144:147], v[192:195], v[76:79]
	v_mfma_f32_16x16x32_bf16 v[120:123], v[148:151], v[164:167], v[120:123]
	v_mfma_f32_16x16x32_bf16 v[116:119], v[156:159], v[164:167], v[116:119]
	v_mfma_f32_16x16x32_bf16 v[104:107], v[148:151], v[172:175], v[104:107]
	v_mfma_f32_16x16x32_bf16 v[100:103], v[156:159], v[172:175], v[100:103]
	v_mfma_f32_16x16x32_bf16 v[88:91], v[148:151], v[180:183], v[88:91]
	v_mfma_f32_16x16x32_bf16 v[84:87], v[156:159], v[180:183], v[84:87]
	v_mfma_f32_16x16x32_bf16 v[72:75], v[148:151], v[188:191], v[72:75]
	v_mfma_f32_16x16x32_bf16 v[68:71], v[156:159], v[188:191], v[68:71]
	v_mfma_f32_16x16x32_bf16 v[120:123], v[152:155], v[168:171], v[120:123]
	v_mfma_f32_16x16x32_bf16 v[116:119], v[160:163], v[168:171], v[116:119]
	v_mfma_f32_16x16x32_bf16 v[104:107], v[152:155], v[176:179], v[104:107]
	v_mfma_f32_16x16x32_bf16 v[100:103], v[160:163], v[176:179], v[100:103]
	v_mfma_f32_16x16x32_bf16 v[88:91], v[152:155], v[184:187], v[88:91]
	v_mfma_f32_16x16x32_bf16 v[84:87], v[160:163], v[184:187], v[84:87]
	v_mfma_f32_16x16x32_bf16 v[72:75], v[152:155], v[192:195], v[72:75]
	v_mfma_f32_16x16x32_bf16 v[68:71], v[160:163], v[192:195], v[68:71]
	s_setprio 0
	s_barrier
	s_add_i32 s12, s14, s70
	v_lshl_add_u64 v[196:197], v[196:197], 0, s[68:69]
	s_mov_b32 m0, s12
	ds_read_b128 v[164:167], v243 offset:49152
	ds_read_b128 v[168:171], v243 offset:50176
	ds_read_b128 v[172:175], v243 offset:51200
	ds_read_b128 v[176:179], v243 offset:52224
	ds_read_b128 v[180:183], v243 offset:53248
	ds_read_b128 v[184:187], v243 offset:54272
	ds_read_b128 v[188:191], v243 offset:55296
	ds_read_b128 v[192:195], v243 offset:56320
	global_load_lds_dwordx4 v[196:197], off
	s_add_i32 m0, s12, 0x2000
	s_add_u32 s12, s40, 0x40080
	v_lshl_add_u64 v[196:197], v[198:199], 0, s[68:69]
	s_addc_u32 s13, s41, 0
	s_add_i32 s14, s15, s70
	global_load_lds_dwordx4 v[196:197], off
	v_lshl_add_u64 v[196:197], s[12:13], 0, v[2:3]
	s_mov_b32 m0, s14
	s_nop 0
	global_load_lds_dwordx4 v[196:197], off
	v_lshl_add_u64 v[196:197], s[12:13], 0, v[218:219]
	s_add_i32 m0, s14, 0x2000
	s_nop 0
	global_load_lds_dwordx4 v[196:197], off
	v_lshl_add_u64 v[196:197], v[200:201], 0, s[68:69]
	s_mov_b32 m0, s85
	s_nop 0
	global_load_lds_dwordx4 v[196:197], off
	v_lshl_add_u64 v[196:197], v[202:203], 0, s[68:69]
	s_mov_b32 m0, s87
	s_nop 0
	global_load_lds_dwordx4 v[196:197], off
	s_waitcnt vmcnt(8)
	s_waitcnt lgkmcnt(0)
	s_barrier
	s_setprio 1
	s_waitcnt lgkmcnt(0)
	v_mfma_f32_16x16x32_bf16 v[64:67], v[124:127], v[164:167], v[64:67]
	v_mfma_f32_16x16x32_bf16 v[60:63], v[136:139], v[164:167], v[60:63]
	v_mfma_f32_16x16x32_bf16 v[48:51], v[124:127], v[172:175], v[48:51]
	v_mfma_f32_16x16x32_bf16 v[44:47], v[136:139], v[172:175], v[44:47]
	v_mfma_f32_16x16x32_bf16 v[32:35], v[124:127], v[180:183], v[32:35]
	v_mfma_f32_16x16x32_bf16 v[28:31], v[136:139], v[180:183], v[28:31]
	v_mfma_f32_16x16x32_bf16 v[16:19], v[124:127], v[188:191], v[16:19]
	v_mfma_f32_16x16x32_bf16 v[12:15], v[136:139], v[188:191], v[12:15]
	v_mfma_f32_16x16x32_bf16 v[64:67], v[128:131], v[168:171], v[64:67]
	v_mfma_f32_16x16x32_bf16 v[60:63], v[144:147], v[168:171], v[60:63]
	v_mfma_f32_16x16x32_bf16 v[48:51], v[128:131], v[176:179], v[48:51]
	v_mfma_f32_16x16x32_bf16 v[44:47], v[144:147], v[176:179], v[44:47]
	v_mfma_f32_16x16x32_bf16 v[32:35], v[128:131], v[184:187], v[32:35]
	v_mfma_f32_16x16x32_bf16 v[28:31], v[144:147], v[184:187], v[28:31]
	v_mfma_f32_16x16x32_bf16 v[16:19], v[128:131], v[192:195], v[16:19]
	v_mfma_f32_16x16x32_bf16 v[12:15], v[144:147], v[192:195], v[12:15]
	v_mfma_f32_16x16x32_bf16 v[56:59], v[148:151], v[164:167], v[56:59]
	v_mfma_f32_16x16x32_bf16 v[52:55], v[156:159], v[164:167], v[52:55]
	v_mfma_f32_16x16x32_bf16 v[40:43], v[148:151], v[172:175], v[40:43]
	v_mfma_f32_16x16x32_bf16 v[36:39], v[156:159], v[172:175], v[36:39]
	v_mfma_f32_16x16x32_bf16 v[24:27], v[148:151], v[180:183], v[24:27]
	v_mfma_f32_16x16x32_bf16 v[20:23], v[156:159], v[180:183], v[20:23]
	v_mfma_f32_16x16x32_bf16 v[8:11], v[148:151], v[188:191], v[8:11]
	v_mfma_f32_16x16x32_bf16 v[4:7], v[156:159], v[188:191], v[4:7]
	v_mfma_f32_16x16x32_bf16 v[56:59], v[152:155], v[168:171], v[56:59]
	v_mfma_f32_16x16x32_bf16 v[52:55], v[160:163], v[168:171], v[52:55]
	v_mfma_f32_16x16x32_bf16 v[40:43], v[152:155], v[176:179], v[40:43]
	v_mfma_f32_16x16x32_bf16 v[36:39], v[160:163], v[176:179], v[36:39]
	v_mfma_f32_16x16x32_bf16 v[24:27], v[152:155], v[184:187], v[24:27]
	v_mfma_f32_16x16x32_bf16 v[20:23], v[160:163], v[184:187], v[20:23]
	v_mfma_f32_16x16x32_bf16 v[8:11], v[152:155], v[192:195], v[8:11]
	v_mfma_f32_16x16x32_bf16 v[4:7], v[160:163], v[192:195], v[4:7]
	s_setprio 0
	s_barrier
	s_add_i32 s11, s11, 2
	s_add_u32 s9, s9, 0x100
	s_addc_u32 s10, s10, 0
	s_add_u32 s38, s38, 0x100
	s_addc_u32 s39, s39, 0
	s_cmp_gt_u32 s11, 13
	s_cbranch_scc0 .LBB0_947
	s_and_b64 vcc, exec, s[46:47]
	s_cbranch_vccz .LBB0_950
	s_barrier

.LBB0_1129:
	s_cmp_eq_u32 s42, 0
	s_cselect_b32 s32, 1, 0
	v_cndmask_b32_e64 v4, 0, 1, s[42:43]
	v_cmp_ne_u32_e64 s[36:37], 1, v4
	s_andn2_b64 vcc, exec, s[42:43]
	s_and_b64 vcc, exec, s[36:37]
	s_mov_b64 s[60:61], s[38:39]
	s_cbranch_vccnz .LBB0_1131
	s_mul_i32 s6, s92, 0x2c0000
	s_mul_hi_i32 s5, s92, 0x2c0000
	s_add_u32 s60, s70, s6
	s_addc_u32 s61, s71, s5

.LBB0_1134:
	s_add_u32 s40, s38, 0x100
	s_addc_u32 s41, s39, 0
	s_add_i32 s8, 0, 0x10000
	s_cmpk_eq_i32 s7, 0x54
	s_cselect_b32 s45, s61, s41
	s_cselect_b32 s44, s60, s40
	s_cselect_b32 s43, s63, s6
	s_cselect_b32 s42, s62, s5
	s_add_i32 s10, 0, 0x14000
	v_add_u32_e32 v112, s8, v242
	v_add_u32_e32 v148, s10, v242
	ds_read_b128 v[92:95], v112
	ds_read_b128 v[100:103], v112 offset:1024
	ds_read_b128 v[108:111], v112 offset:2048
	ds_read_b128 v[112:115], v112 offset:3072
	ds_read_b128 v[116:119], v148
	ds_read_b128 v[128:131], v148 offset:1024
	ds_read_b128 v[140:143], v148 offset:2048
	ds_read_b128 v[148:151], v148 offset:3072
	v_lshl_add_u64 v[196:197], s[38:39], 0, v[222:223]
	s_add_i32 m0, s83, 0xc000
	ds_read_b128 v[160:163], v245
	ds_read_b128 v[168:171], v245 offset:1024
	ds_read_b128 v[172:175], v245 offset:2048
	ds_read_b128 v[176:179], v245 offset:3072
	ds_read_b128 v[180:183], v245 offset:4096
	ds_read_b128 v[184:187], v245 offset:5120
	ds_read_b128 v[188:191], v245 offset:6144
	ds_read_b128 v[192:195], v245 offset:7168
	global_load_lds_dwordx4 v[196:197], off
	v_lshl_add_u64 v[196:197], s[38:39], 0, v[220:221]
	s_add_i32 m0, s83, 0xe000
	s_nop 0
	global_load_lds_dwordx4 v[196:197], off
	s_cmp_lg_u32 s32, 0
	s_cbranch_scc1 .Lrd_skip1
	s_waitcnt vmcnt(8)
.Lrd_skip1:
	s_waitcnt lgkmcnt(0)
	s_barrier
	s_setprio 1
	s_waitcnt lgkmcnt(0)
	v_mfma_f32_16x16x32_bf16 v[164:167], v[92:95], v[160:163], v[164:167]
	v_mfma_f32_16x16x32_bf16 v[156:159], v[108:111], v[160:163], v[156:159]
	v_mfma_f32_16x16x32_bf16 v[136:139], v[92:95], v[172:175], v[136:139]
	v_mfma_f32_16x16x32_bf16 v[132:135], v[108:111], v[172:175], v[132:135]
	v_mfma_f32_16x16x32_bf16 v[104:107], v[92:95], v[180:183], v[104:107]
	v_mfma_f32_16x16x32_bf16 v[96:99], v[108:111], v[180:183], v[96:99]
	v_mfma_f32_16x16x32_bf16 v[80:83], v[92:95], v[188:191], v[80:83]
	v_mfma_f32_16x16x32_bf16 v[76:79], v[108:111], v[188:191], v[76:79]
	v_mfma_f32_16x16x32_bf16 v[164:167], v[100:103], v[168:171], v[164:167]
	v_mfma_f32_16x16x32_bf16 v[156:159], v[112:115], v[168:171], v[156:159]
	v_mfma_f32_16x16x32_bf16 v[136:139], v[100:103], v[176:179], v[136:139]
	v_mfma_f32_16x16x32_bf16 v[132:135], v[112:115], v[176:179], v[132:135]
	v_mfma_f32_16x16x32_bf16 v[104:107], v[100:103], v[184:187], v[104:107]
	v_mfma_f32_16x16x32_bf16 v[96:99], v[112:115], v[184:187], v[96:99]
	v_mfma_f32_16x16x32_bf16 v[80:83], v[100:103], v[192:195], v[80:83]
	v_mfma_f32_16x16x32_bf16 v[76:79], v[112:115], v[192:195], v[76:79]
	v_mfma_f32_16x16x32_bf16 v[152:155], v[116:119], v[160:163], v[152:155]
	v_mfma_f32_16x16x32_bf16 v[144:147], v[140:143], v[160:163], v[144:147]
	v_mfma_f32_16x16x32_bf16 v[124:127], v[116:119], v[172:175], v[124:127]
	v_mfma_f32_16x16x32_bf16 v[120:123], v[140:143], v[172:175], v[120:123]
	v_mfma_f32_16x16x32_bf16 v[88:91], v[116:119], v[180:183], v[88:91]
	v_mfma_f32_16x16x32_bf16 v[84:87], v[140:143], v[180:183], v[84:87]
	v_mfma_f32_16x16x32_bf16 v[72:75], v[116:119], v[188:191], v[72:75]
	v_mfma_f32_16x16x32_bf16 v[68:71], v[140:143], v[188:191], v[68:71]
	v_mfma_f32_16x16x32_bf16 v[152:155], v[128:131], v[168:171], v[152:155]
	v_mfma_f32_16x16x32_bf16 v[144:147], v[148:151], v[168:171], v[144:147]
	v_mfma_f32_16x16x32_bf16 v[124:127], v[128:131], v[176:179], v[124:127]
	v_mfma_f32_16x16x32_bf16 v[120:123], v[148:151], v[176:179], v[120:123]
	v_mfma_f32_16x16x32_bf16 v[88:91], v[128:131], v[184:187], v[88:91]
	v_mfma_f32_16x16x32_bf16 v[84:87], v[148:151], v[184:187], v[84:87]
	v_mfma_f32_16x16x32_bf16 v[72:75], v[128:131], v[192:195], v[72:75]
	v_mfma_f32_16x16x32_bf16 v[68:71], v[148:151], v[192:195], v[68:71]
	s_setprio 0
	s_barrier
	s_add_i32 s8, s8, s82
	v_lshl_add_u64 v[196:197], s[42:43], 0, v[2:3]
	s_mov_b32 m0, s8
	ds_read_b128 v[160:163], v245 offset:16384
	ds_read_b128 v[168:171], v245 offset:17408
	ds_read_b128 v[172:175], v245 offset:18432
	ds_read_b128 v[176:179], v245 offset:19456
	ds_read_b128 v[180:183], v245 offset:20480
	ds_read_b128 v[184:187], v245 offset:21504
	ds_read_b128 v[188:191], v245 offset:22528
	ds_read_b128 v[192:195], v245 offset:23552
	global_load_lds_dwordx4 v[196:197], off
	s_add_i32 m0, s8, 0x2000
	s_add_u32 s8, s42, 0x160000
	v_lshl_add_u64 v[198:199], s[42:43], 0, v[218:219]
	s_addc_u32 s9, s43, 0
	s_add_i32 s10, s10, s82
	global_load_lds_dwordx4 v[198:199], off
	v_lshl_add_u64 v[200:201], s[8:9], 0, v[2:3]
	s_mov_b32 m0, s10
	v_lshl_add_u64 v[202:203], s[44:45], 0, v[216:217]
	global_load_lds_dwordx4 v[200:201], off
	v_lshl_add_u64 v[200:201], s[8:9], 0, v[218:219]
	s_add_i32 m0, s10, 0x2000
	s_nop 0
	global_load_lds_dwordx4 v[200:201], off
	v_lshl_add_u64 v[200:201], s[44:45], 0, v[0:1]
	s_mov_b32 m0, s83
	s_nop 0
	global_load_lds_dwordx4 v[200:201], off
	s_mov_b32 m0, s84
	s_nop 0
	global_load_lds_dwordx4 v[202:203], off
	s_cmp_lg_u32 s32, 0
	s_cbranch_scc1 .Lrd_skip2
	s_waitcnt vmcnt(8)
.Lrd_skip2:
	s_mov_b32 s32, 0
	s_waitcnt lgkmcnt(0)
	s_barrier
	s_setprio 1
	s_waitcnt lgkmcnt(0)
	v_mfma_f32_16x16x32_bf16 v[64:67], v[92:95], v[160:163], v[64:67]
	v_mfma_f32_16x16x32_bf16 v[60:63], v[108:111], v[160:163], v[60:63]
	v_mfma_f32_16x16x32_bf16 v[48:51], v[92:95], v[172:175], v[48:51]
	v_mfma_f32_16x16x32_bf16 v[44:47], v[108:111], v[172:175], v[44:47]
	v_mfma_f32_16x16x32_bf16 v[32:35], v[92:95], v[180:183], v[32:35]
	v_mfma_f32_16x16x32_bf16 v[28:31], v[108:111], v[180:183], v[28:31]
	v_mfma_f32_16x16x32_bf16 v[16:19], v[92:95], v[188:191], v[16:19]
	v_mfma_f32_16x16x32_bf16 v[12:15], v[108:111], v[188:191], v[12:15]
	v_mfma_f32_16x16x32_bf16 v[64:67], v[100:103], v[168:171], v[64:67]
	v_mfma_f32_16x16x32_bf16 v[60:63], v[112:115], v[168:171], v[60:63]
	v_mfma_f32_16x16x32_bf16 v[48:51], v[100:103], v[176:179], v[48:51]
	v_mfma_f32_16x16x32_bf16 v[44:47], v[112:115], v[176:179], v[44:47]
	v_mfma_f32_16x16x32_bf16 v[32:35], v[100:103], v[184:187], v[32:35]
	v_mfma_f32_16x16x32_bf16 v[28:31], v[112:115], v[184:187], v[28:31]
	v_mfma_f32_16x16x32_bf16 v[16:19], v[100:103], v[192:195], v[16:19]
	v_mfma_f32_16x16x32_bf16 v[12:15], v[112:115], v[192:195], v[12:15]
	v_mfma_f32_16x16x32_bf16 v[56:59], v[116:119], v[160:163], v[56:59]
	v_mfma_f32_16x16x32_bf16 v[52:55], v[140:143], v[160:163], v[52:55]
	v_mfma_f32_16x16x32_bf16 v[40:43], v[116:119], v[172:175], v[40:43]
	v_mfma_f32_16x16x32_bf16 v[36:39], v[140:143], v[172:175], v[36:39]
	v_mfma_f32_16x16x32_bf16 v[24:27], v[116:119], v[180:183], v[24:27]
	v_mfma_f32_16x16x32_bf16 v[20:23], v[140:143], v[180:183], v[20:23]
	v_mfma_f32_16x16x32_bf16 v[8:11], v[116:119], v[188:191], v[8:11]
	v_mfma_f32_16x16x32_bf16 v[4:7], v[140:143], v[188:191], v[4:7]
	v_mfma_f32_16x16x32_bf16 v[56:59], v[128:131], v[168:171], v[56:59]
	v_mfma_f32_16x16x32_bf16 v[52:55], v[148:151], v[168:171], v[52:55]
	v_mfma_f32_16x16x32_bf16 v[40:43], v[128:131], v[176:179], v[40:43]
	v_mfma_f32_16x16x32_bf16 v[36:39], v[148:151], v[176:179], v[36:39]
	v_mfma_f32_16x16x32_bf16 v[24:27], v[128:131], v[184:187], v[24:27]
	v_mfma_f32_16x16x32_bf16 v[20:23], v[148:151], v[184:187], v[20:23]
	v_mfma_f32_16x16x32_bf16 v[8:11], v[128:131], v[192:195], v[8:11]
	v_mfma_f32_16x16x32_bf16 v[4:7], v[148:151], v[192:195], v[4:7]
	s_setprio 0
	s_barrier
	s_add_i32 s10, 0, 0x18000
	s_add_i32 s11, 0, 0x1c000
	v_add_u32_e32 v112, s10, v242
	v_add_u32_e32 v148, s11, v242
	ds_read_b128 v[92:95], v112
	ds_read_b128 v[100:103], v112 offset:1024
	ds_read_b128 v[108:111], v112 offset:2048
	ds_read_b128 v[112:115], v112 offset:3072
	ds_read_b128 v[116:119], v148
	ds_read_b128 v[128:131], v148 offset:1024
	ds_read_b128 v[140:143], v148 offset:2048
	ds_read_b128 v[148:151], v148 offset:3072
	s_add_u32 s8, s44, 0x160000
	s_addc_u32 s9, s45, 0
	s_mov_b32 m0, s85
	v_lshl_add_u64 v[204:205], s[8:9], 0, v[0:1]
	ds_read_b128 v[160:163], v245 offset:32768
	ds_read_b128 v[168:171], v245 offset:33792
	ds_read_b128 v[172:175], v245 offset:34816
	ds_read_b128 v[176:179], v245 offset:35840
	ds_read_b128 v[180:183], v245 offset:36864
	ds_read_b128 v[184:187], v245 offset:37888
	ds_read_b128 v[188:191], v245 offset:38912
	ds_read_b128 v[192:195], v245 offset:39936
	global_load_lds_dwordx4 v[204:205], off
	v_lshl_add_u64 v[204:205], s[8:9], 0, v[216:217]
	s_mov_b32 m0, s87
	s_nop 0
	global_load_lds_dwordx4 v[204:205], off
	s_waitcnt vmcnt(8)
	s_waitcnt lgkmcnt(0)
	s_barrier
	s_setprio 1
	s_waitcnt lgkmcnt(0)
	v_mfma_f32_16x16x32_bf16 v[164:167], v[92:95], v[160:163], v[164:167]
	v_mfma_f32_16x16x32_bf16 v[156:159], v[108:111], v[160:163], v[156:159]
	v_mfma_f32_16x16x32_bf16 v[136:139], v[92:95], v[172:175], v[136:139]
	v_mfma_f32_16x16x32_bf16 v[132:135], v[108:111], v[172:175], v[132:135]
	v_mfma_f32_16x16x32_bf16 v[104:107], v[92:95], v[180:183], v[104:107]
	v_mfma_f32_16x16x32_bf16 v[96:99], v[108:111], v[180:183], v[96:99]
	v_mfma_f32_16x16x32_bf16 v[80:83], v[92:95], v[188:191], v[80:83]
	v_mfma_f32_16x16x32_bf16 v[76:79], v[108:111], v[188:191], v[76:79]
	v_mfma_f32_16x16x32_bf16 v[164:167], v[100:103], v[168:171], v[164:167]
	v_mfma_f32_16x16x32_bf16 v[156:159], v[112:115], v[168:171], v[156:159]
	v_mfma_f32_16x16x32_bf16 v[136:139], v[100:103], v[176:179], v[136:139]
	v_mfma_f32_16x16x32_bf16 v[132:135], v[112:115], v[176:179], v[132:135]
	v_mfma_f32_16x16x32_bf16 v[104:107], v[100:103], v[184:187], v[104:107]
	v_mfma_f32_16x16x32_bf16 v[96:99], v[112:115], v[184:187], v[96:99]
	v_mfma_f32_16x16x32_bf16 v[80:83], v[100:103], v[192:195], v[80:83]
	v_mfma_f32_16x16x32_bf16 v[76:79], v[112:115], v[192:195], v[76:79]
	v_mfma_f32_16x16x32_bf16 v[152:155], v[116:119], v[160:163], v[152:155]
	v_mfma_f32_16x16x32_bf16 v[144:147], v[140:143], v[160:163], v[144:147]
	v_mfma_f32_16x16x32_bf16 v[124:127], v[116:119], v[172:175], v[124:127]
	v_mfma_f32_16x16x32_bf16 v[120:123], v[140:143], v[172:175], v[120:123]
	v_mfma_f32_16x16x32_bf16 v[88:91], v[116:119], v[180:183], v[88:91]
	v_mfma_f32_16x16x32_bf16 v[84:87], v[140:143], v[180:183], v[84:87]
	v_mfma_f32_16x16x32_bf16 v[72:75], v[116:119], v[188:191], v[72:75]
	v_mfma_f32_16x16x32_bf16 v[68:71], v[140:143], v[188:191], v[68:71]
	v_mfma_f32_16x16x32_bf16 v[152:155], v[128:131], v[168:171], v[152:155]
	v_mfma_f32_16x16x32_bf16 v[144:147], v[148:151], v[168:171], v[144:147]
	v_mfma_f32_16x16x32_bf16 v[124:127], v[128:131], v[176:179], v[124:127]
	v_mfma_f32_16x16x32_bf16 v[120:123], v[148:151], v[176:179], v[120:123]
	v_mfma_f32_16x16x32_bf16 v[88:91], v[128:131], v[184:187], v[88:91]
	v_mfma_f32_16x16x32_bf16 v[84:87], v[148:151], v[184:187], v[84:87]
	v_mfma_f32_16x16x32_bf16 v[72:75], v[128:131], v[192:195], v[72:75]
	v_mfma_f32_16x16x32_bf16 v[68:71], v[148:151], v[192:195], v[68:71]
	s_setprio 0
	s_barrier
	s_add_i32 s8, s10, s82
	v_lshl_add_u64 v[196:197], v[196:197], 0, s[68:69]
	s_mov_b32 m0, s8
	ds_read_b128 v[160:163], v245 offset:49152
	ds_read_b128 v[168:171], v245 offset:50176
	ds_read_b128 v[172:175], v245 offset:51200
	ds_read_b128 v[176:179], v245 offset:52224
	ds_read_b128 v[180:183], v245 offset:53248
	ds_read_b128 v[184:187], v245 offset:54272
	ds_read_b128 v[188:191], v245 offset:55296
	ds_read_b128 v[192:195], v245 offset:56320
	global_load_lds_dwordx4 v[196:197], off
	s_add_i32 m0, s8, 0x2000
	s_add_u32 s8, s42, 0x160080
	v_lshl_add_u64 v[196:197], v[198:199], 0, s[68:69]
	s_addc_u32 s9, s43, 0
	s_add_i32 s10, s11, s82
	global_load_lds_dwordx4 v[196:197], off
	v_lshl_add_u64 v[196:197], s[8:9], 0, v[2:3]
	s_mov_b32 m0, s10
	s_nop 0
	global_load_lds_dwordx4 v[196:197], off
	v_lshl_add_u64 v[196:197], s[8:9], 0, v[218:219]
	s_add_i32 m0, s10, 0x2000
	s_nop 0
	global_load_lds_dwordx4 v[196:197], off
	v_lshl_add_u64 v[196:197], v[200:201], 0, s[68:69]
	s_mov_b32 m0, s72
	s_nop 0
	global_load_lds_dwordx4 v[196:197], off
	v_lshl_add_u64 v[196:197], v[202:203], 0, s[68:69]
	s_mov_b32 m0, s88
	s_nop 0
	global_load_lds_dwordx4 v[196:197], off
	s_waitcnt vmcnt(8)
	s_waitcnt lgkmcnt(0)
	s_barrier
	s_setprio 1
	s_waitcnt lgkmcnt(0)
	v_mfma_f32_16x16x32_bf16 v[64:67], v[92:95], v[160:163], v[64:67]
	v_mfma_f32_16x16x32_bf16 v[60:63], v[108:111], v[160:163], v[60:63]
	v_mfma_f32_16x16x32_bf16 v[48:51], v[92:95], v[172:175], v[48:51]
	v_mfma_f32_16x16x32_bf16 v[44:47], v[108:111], v[172:175], v[44:47]
	v_mfma_f32_16x16x32_bf16 v[32:35], v[92:95], v[180:183], v[32:35]
	v_mfma_f32_16x16x32_bf16 v[28:31], v[108:111], v[180:183], v[28:31]
	v_mfma_f32_16x16x32_bf16 v[16:19], v[92:95], v[188:191], v[16:19]
	v_mfma_f32_16x16x32_bf16 v[12:15], v[108:111], v[188:191], v[12:15]
	v_mfma_f32_16x16x32_bf16 v[64:67], v[100:103], v[168:171], v[64:67]
	v_mfma_f32_16x16x32_bf16 v[60:63], v[112:115], v[168:171], v[60:63]
	v_mfma_f32_16x16x32_bf16 v[48:51], v[100:103], v[176:179], v[48:51]
	v_mfma_f32_16x16x32_bf16 v[44:47], v[112:115], v[176:179], v[44:47]
	v_mfma_f32_16x16x32_bf16 v[32:35], v[100:103], v[184:187], v[32:35]
	v_mfma_f32_16x16x32_bf16 v[28:31], v[112:115], v[184:187], v[28:31]
	v_mfma_f32_16x16x32_bf16 v[16:19], v[100:103], v[192:195], v[16:19]
	v_mfma_f32_16x16x32_bf16 v[12:15], v[112:115], v[192:195], v[12:15]
	v_mfma_f32_16x16x32_bf16 v[56:59], v[116:119], v[160:163], v[56:59]
	v_mfma_f32_16x16x32_bf16 v[52:55], v[140:143], v[160:163], v[52:55]
	v_mfma_f32_16x16x32_bf16 v[40:43], v[116:119], v[172:175], v[40:43]
	v_mfma_f32_16x16x32_bf16 v[36:39], v[140:143], v[172:175], v[36:39]
	v_mfma_f32_16x16x32_bf16 v[24:27], v[116:119], v[180:183], v[24:27]
	v_mfma_f32_16x16x32_bf16 v[20:23], v[140:143], v[180:183], v[20:23]
	v_mfma_f32_16x16x32_bf16 v[8:11], v[116:119], v[188:191], v[8:11]
	v_mfma_f32_16x16x32_bf16 v[4:7], v[140:143], v[188:191], v[4:7]
	v_mfma_f32_16x16x32_bf16 v[56:59], v[128:131], v[168:171], v[56:59]
	v_mfma_f32_16x16x32_bf16 v[52:55], v[148:151], v[168:171], v[52:55]
	v_mfma_f32_16x16x32_bf16 v[40:43], v[128:131], v[176:179], v[40:43]
	v_mfma_f32_16x16x32_bf16 v[36:39], v[148:151], v[176:179], v[36:39]
	v_mfma_f32_16x16x32_bf16 v[24:27], v[128:131], v[184:187], v[24:27]
	v_mfma_f32_16x16x32_bf16 v[20:23], v[148:151], v[184:187], v[20:23]
	v_mfma_f32_16x16x32_bf16 v[8:11], v[128:131], v[192:195], v[8:11]
	v_mfma_f32_16x16x32_bf16 v[4:7], v[148:151], v[192:195], v[4:7]
	s_setprio 0
	s_barrier
	s_add_i32 s7, s7, 2
	s_add_u32 s5, s5, 0x100
	s_addc_u32 s6, s6, 0
	s_cmpk_gt_u32 s7, 0x55
	s_mov_b64 s[38:39], s[40:41]
	s_cbranch_scc0 .LBB0_1134
	s_and_b64 vcc, exec, s[52:53]
	s_cbranch_vccz .LBB0_1137
	s_barrier
